# MoBA prologue: first own-block K/V tile requested at item top (copied in after the routing prologue)
# speedup vs baseline: 1.0015x; 1.0015x over previous
.LBB0_331:
	v_mov_b32_e32 v8, v254
	v_add_u32_e32 v254, v254, v255
	s_mov_b64 s[2:3], -1
	v_cmp_gt_i32_e32 vcc, 64, v8
	s_and_saveexec_b64 s[82:83], vcc
	s_cbranch_execz .LBB0_330
	v_ashrrev_i32_e32 v33, 2, v8
	v_sub_u32_e32 v7, 15, v33
	v_mov_b32_e32 v3, v197
	v_lshlrev_b32_e32 v0, 5, v8
	v_readlane_b32 s2, v249, 37
	v_lshlrev_b32_e32 v9, 6, v7
	s_nop 0
	v_and_or_b32 v32, v0, 64, s2
	v_cmp_lt_i32_e32 vcc, v3, v9
	s_barrier
	v_and_b32_e32 v216, 1, v8
	v_readlane_b32 s2, v249, 36
	v_lshlrev_b32_e32 v217, 7, v216
	v_ashrrev_i32_e32 v218, 1, v3
	v_lshl_add_u32 v219, v7, 8, s2
	v_lshl_add_u32 v224, v7, 8, s2
	v_or_b32_e32 v219, v219, v217
	v_add_u32_e32 v218, v218, v219
	v_mov_b64_e32 v[220:221], s[4:5]
	v_mad_i64_i32 v[220:221], s[2:3], v218, s93, v[220:221]
	v_lshlrev_b32_e32 v222, 1, v32
	v_mov_b32_e32 v223, v2
	v_lshl_add_u64 v[220:221], v[220:221], 0, v[222:223]
	global_load_dwordx4 v[154:157], v[220:221], off
	global_load_dwordx4 v[158:161], v[220:221], off offset:16
	global_load_dwordx4 v[162:165], v[220:221], off offset:32
	global_load_dwordx4 v[166:169], v[220:221], off offset:48
	global_load_dwordx4 v[170:173], v[220:221], off offset:64
	global_load_dwordx4 v[174:177], v[220:221], off offset:80
	global_load_dwordx4 v[178:181], v[220:221], off offset:96
	global_load_dwordx4 v[182:185], v[220:221], off offset:112
	v_ashrrev_i32_e32 v225, 2, v3
	v_add_u32_e32 v224, v224, v225
	v_mov_b64_e32 v[226:227], s[4:5]
	v_mad_i64_i32 v[226:227], s[2:3], v224, s93, v[226:227]
	v_lshlrev_b32_e32 v228, 4, v3
	v_and_b32_e32 v228, 48, v228
	v_lshlrev_b32_e32 v228, 1, v228
	v_mov_b32_e32 v229, v2
	v_lshl_add_u64 v[226:227], v[226:227], 0, v[228:229]
	v_lshl_add_u64 v[226:227], v[226:227], 0, v[222:223]
	global_load_dwordx4 v[232:235], v[226:227], off offset:528
	global_load_dwordx4 v[236:239], v[226:227], off offset:512
	global_load_dwordx4 v[240:243], v[226:227], off offset:1040
	global_load_dwordx4 v[244:247], v[226:227], off offset:1024
	s_and_saveexec_b64 s[2:3], vcc
	s_cbranch_execz .LBB0_344
	v_readlane_b32 s8, v249, 38
	v_lshlrev_b32_e32 v0, 2, v32
	v_mov_b32_e32 v1, v2
	v_readlane_b32 s9, v249, 39
	v_and_b32_e32 v4, 63, v3
	v_lshlrev_b32_e32 v4, 2, v4
	v_lshl_add_u64 v[0:1], s[8:9], 0, v[0:1]
	v_mov_b32_e32 v5, v2
	v_lshl_add_u64 v[0:1], v[0:1], 0, v[4:5]
	v_add_u32_e32 v5, 0x100, v3
	v_max_i32_e32 v4, v9, v5
	v_xad_u32 v12, v3, -1, v4
	s_movk_i32 s8, 0xff
	v_cmp_lt_u32_e32 vcc, s8, v12
	s_mov_b64 s[10:11], -1
	v_mov_b32_e32 v4, v3
	s_and_saveexec_b64 s[8:9], vcc
	s_cbranch_execz .LBB0_341
	v_lshrrev_b32_e32 v4, 8, v12
	v_add_u32_e32 v12, 1, v4
	v_and_b32_e32 v13, 0x1fffffe, v12
	v_mov_b32_e32 v4, v3
	v_lshl_add_u32 v15, v3, 2, v210
	s_mov_b64 s[10:11], 0
	v_mov_b32_e32 v16, v13
	v_readlane_b32 s15, v248, 5

.LBB0_398:
	s_or_b64 exec, exec, s[2:3]
	v_mov_b32_e32 v117, 0
	s_waitcnt lgkmcnt(0)
	s_barrier
	ds_read_b32 v0, v117 offset:56960
	v_ashrrev_i32_e32 v7, 2, v3
	v_and_b32_e32 v16, 48, v22
	v_lshlrev_b32_e32 v12, 1, v16
	v_mov_b32_e32 v13, v2
	s_waitcnt lgkmcnt(0)
	v_add_u32_e32 v4, v0, v7
	v_mov_b64_e32 v[0:1], s[4:5]
	v_mad_i64_i32 v[0:1], s[2:3], v4, s93, v[0:1]
	v_lshl_add_u64 v[4:5], v[0:1], 0, v[12:13]
	v_lshlrev_b32_e32 v0, 1, v32
	v_mov_b32_e32 v1, v2
	v_lshl_add_u64 v[4:5], v[4:5], 0, v[0:1]
	s_waitcnt vmcnt(0)
	v_mov_b64_e32 v[20:21], v[232:233]
	v_mov_b64_e32 v[22:23], v[234:235]
	v_mov_b64_e32 v[24:25], v[236:237]
	v_mov_b64_e32 v[26:27], v[238:239]
	v_mov_b64_e32 v[28:29], v[240:241]
	v_mov_b64_e32 v[30:31], v[242:243]
	v_mov_b64_e32 v[32:33], v[244:245]
	v_mov_b64_e32 v[34:35], v[246:247]
	ds_read_b64 v[4:5], v117 offset:59008
	v_ashrrev_i32_e32 v8, 6, v3
	v_and_b32_e32 v15, 15, v3
	v_bfe_u32 v3, v3, 4, 2
	s_mov_b64 s[44:45], 0
	s_waitcnt lgkmcnt(0)
	v_readfirstlane_b32 s10, v5
	v_readfirstlane_b32 s14, v4
	s_cmp_lt_i32 s10, s14
	s_cselect_b64 s[48:49], -1, 0
	s_cmp_ge_i32 s10, s14
	v_lshlrev_b32_e32 v19, 4, v8
	s_mov_b64 s[46:47], 0
	v_mov_b32_e32 v129, 0
	s_cbranch_scc1 .LBB0_402
	s_lshl_b32 s2, s10, 4
	v_mov_b32_e32 v4, s2
	v_add_u32_e32 v4, 0xdc00, v4
	ds_read2_b32 v[4:5], v4 offset0:161 offset1:163
	v_mov_b32_e32 v129, 0
	s_waitcnt lgkmcnt(0)
	v_lshlrev_b32_e32 v9, 2, v5
	ds_read_b32 v9, v9 offset:56832
	v_lshl_add_u32 v4, v4, 6, v19
	s_waitcnt lgkmcnt(0)
	v_cmp_lt_i32_e32 vcc, v4, v9
	s_and_saveexec_b64 s[2:3], vcc
	s_cbranch_execz .LBB0_401
	v_lshlrev_b32_e32 v5, 7, v5
	v_add3_u32 v4, v5, v4, v15
	ds_read_u8 v4, v4 offset:54784
	s_movk_i32 s8, 0xff
	v_mov_b32_e32 v36, v0
	v_mov_b32_e32 v37, v2
	s_mov_b64 s[44:45], exec
	s_waitcnt lgkmcnt(0)
	v_cmp_ne_u16_e32 vcc, s8, v4
	s_and_b64 s[46:47], vcc, exec
	s_nop 0
	v_cndmask_b32_e32 v4, 0, v4, vcc
	v_and_b32_e32 v129, 0xffff, v4
	v_add_u32_e32 v9, v128, v129
	v_mov_b64_e32 v[4:5], s[4:5]
	v_mad_u64_u32 v[4:5], s[8:9], v9, s93, v[4:5]
	v_lshl_add_u64 v[4:5], v[4:5], 0, v[36:37]
	v_lshlrev_b32_e32 v36, 4, v3
	v_lshl_add_u64 v[4:5], v[4:5], 0, v[36:37]
	global_load_dwordx4 v[40:43], v[4:5], off
	global_load_dwordx4 v[36:39], v[4:5], off offset:64
